# WY producer step 1: K image bf16 conversion with v_cvt_pk_bf16_f32 (one per two rows) instead of the bfe/add3 bit trick per row
# baseline (speedup 1.0000x reference)
; __device__ __forceinline__ float bf2f(bf16 v) { return __uint_as_float(((unsigned)v) << 16); }
; __device__ __forceinline__ float siluf_(float x) { return x / (1.0f + __expf(-x)); }
; __device__ __forceinline__ int wy_producer_task(const Ctx& c, int l, int tk, WyPre& P, unsigned* head) {
;     ...
; #pragma unroll
;     for (int j = 0; j < 3; ++j) { float xv[11];
; #pragma unroll
;         for (int r = 0; r < 11; ++r) xv[r] = bf2f((bf16)P.hx[j][r]);
; #pragma unroll
;         for (int r = 0; r < 8; ++r) { const int i = 8 * wid + r;
;             float y = siluf_(P.cw[j][0] * xv[r] + P.cw[j][1] * xv[r + 1] + P.cw[j][2] * xv[r + 2] + P.cw[j][3] * xv[r + 3]);
;             if (j < 2) y *= rsqrtf(wave_sum_fast(y * y) + RMS_EPS) * (j == 0 ? 0.125f : 1.0f);
;             if (j == 0) QF[i * 65 + lane] = y;
.LBB0_964:
	s_or_b64 exec, exec, s[2:3]
	v_readlane_b32 s1, v254, 46
	v_lshlrev_b32_e32 v2, 2, v88
	v_lshrrev_b32_e32 v4, 3, v88
	v_and_b32_e32 v5, 7, v88
	s_mul_i32 s2, s1, 0x820
	s_lshl_b32 s3, s1, 7
	v_lshlrev_b32_e32 v4, 10, v4
	v_add_u32_e32 v2, s2, v2
	v_lshl_add_u32 v4, v5, 1, v4
	v_add_u32_e32 v2, 0x400, v2
	v_add_u32_e32 v4, s3, v4
	v_add_u32_e32 v3, 0x11900, v2
	v_add_u32_e32 v4, 0x15e00, v4
	v_mov_b32_e32 v66, 0xbfb8aa3b
	v_mov_b32_e32 v67, 1.0
	v_and_b32_e32 v20, 0xffff0000, v114
	v_lshlrev_b32_e32 v21, 16, v114
	v_and_b32_e32 v22, 0xffff0000, v89
	v_lshlrev_b32_e32 v23, 16, v89
	v_and_b32_e32 v24, 0xffff0000, v115
	v_lshlrev_b32_e32 v25, 16, v115
	v_and_b32_e32 v26, 0xffff0000, v116
	v_lshlrev_b32_e32 v27, 16, v116
	v_and_b32_e32 v28, 0xffff0000, v117
	v_lshlrev_b32_e32 v29, 16, v117
	v_lshlrev_b32_e32 v30, 16, v94
	v_mul_f32_e32 v32, v85, v20
	v_mul_f32_e32 v33, v85, v21
	v_mul_f32_e32 v34, v85, v22
	v_mul_f32_e32 v35, v85, v23
	v_mul_f32_e32 v36, v85, v24
	v_mul_f32_e32 v37, v85, v25
	v_mul_f32_e32 v38, v85, v26
	v_mul_f32_e32 v39, v85, v27
	v_fmac_f32_e32 v32, v84, v21
	v_fmac_f32_e32 v33, v84, v22
	v_fmac_f32_e32 v34, v84, v23
	v_fmac_f32_e32 v35, v84, v24
	v_fmac_f32_e32 v36, v84, v25
	v_fmac_f32_e32 v37, v84, v26
	v_fmac_f32_e32 v38, v84, v27
	v_fmac_f32_e32 v39, v84, v28
	v_fmac_f32_e32 v32, v87, v22
	v_fmac_f32_e32 v33, v87, v23
	v_fmac_f32_e32 v34, v87, v24
	v_fmac_f32_e32 v35, v87, v25
	v_fmac_f32_e32 v36, v87, v26
	v_fmac_f32_e32 v37, v87, v27
	v_fmac_f32_e32 v38, v87, v28
	v_fmac_f32_e32 v39, v87, v29
	v_fmac_f32_e32 v32, v86, v23
	v_fmac_f32_e32 v33, v86, v24
	v_fmac_f32_e32 v34, v86, v25
	v_fmac_f32_e32 v35, v86, v26
	v_fmac_f32_e32 v36, v86, v27
	v_fmac_f32_e32 v37, v86, v28
	v_fmac_f32_e32 v38, v86, v29
	v_fmac_f32_e32 v39, v86, v30
	v_pk_mul_f32 v[40:41], v[32:33], v[66:67] op_sel_hi:[1,0]
	v_pk_mul_f32 v[42:43], v[34:35], v[66:67] op_sel_hi:[1,0]
	v_pk_mul_f32 v[44:45], v[36:37], v[66:67] op_sel_hi:[1,0]
	v_pk_mul_f32 v[46:47], v[38:39], v[66:67] op_sel_hi:[1,0]
	v_exp_f32_e32 v40, v40
	v_exp_f32_e32 v41, v41
	v_exp_f32_e32 v42, v42
	v_exp_f32_e32 v43, v43
	v_exp_f32_e32 v44, v44
	v_exp_f32_e32 v45, v45
	v_exp_f32_e32 v46, v46
	v_exp_f32_e32 v47, v47
	v_pk_add_f32 v[40:41], v[40:41], v[66:67] op_sel:[0,1] op_sel_hi:[1,1]
	v_pk_add_f32 v[42:43], v[42:43], v[66:67] op_sel:[0,1] op_sel_hi:[1,1]
	v_pk_add_f32 v[44:45], v[44:45], v[66:67] op_sel:[0,1] op_sel_hi:[1,1]
	v_pk_add_f32 v[46:47], v[46:47], v[66:67] op_sel:[0,1] op_sel_hi:[1,1]
	v_rcp_f32_e32 v40, v40
	v_rcp_f32_e32 v41, v41
	v_rcp_f32_e32 v42, v42
	v_rcp_f32_e32 v43, v43
	v_rcp_f32_e32 v44, v44
	v_rcp_f32_e32 v45, v45
	v_rcp_f32_e32 v46, v46
	v_rcp_f32_e32 v47, v47
	v_pk_mul_f32 v[32:33], v[32:33], v[40:41]
	v_pk_mul_f32 v[34:35], v[34:35], v[42:43]
	v_pk_mul_f32 v[36:37], v[36:37], v[44:45]
	v_pk_mul_f32 v[38:39], v[38:39], v[46:47]
	v_pk_mul_f32 v[48:49], v[32:33], v[32:33]
	v_pk_mul_f32 v[50:51], v[34:35], v[34:35]
	v_pk_mul_f32 v[52:53], v[36:37], v[36:37]
	v_pk_mul_f32 v[54:55], v[38:39], v[38:39]
	v_add_f32_dpp v48, v48, v48 quad_perm:[1,0,3,2] row_mask:0xf bank_mask:0xf bound_ctrl:1
	v_add_f32_dpp v49, v49, v49 quad_perm:[1,0,3,2] row_mask:0xf bank_mask:0xf bound_ctrl:1
	v_add_f32_dpp v50, v50, v50 quad_perm:[1,0,3,2] row_mask:0xf bank_mask:0xf bound_ctrl:1
	v_add_f32_dpp v51, v51, v51 quad_perm:[1,0,3,2] row_mask:0xf bank_mask:0xf bound_ctrl:1
	v_add_f32_dpp v52, v52, v52 quad_perm:[1,0,3,2] row_mask:0xf bank_mask:0xf bound_ctrl:1
	v_add_f32_dpp v53, v53, v53 quad_perm:[1,0,3,2] row_mask:0xf bank_mask:0xf bound_ctrl:1
	v_add_f32_dpp v54, v54, v54 quad_perm:[1,0,3,2] row_mask:0xf bank_mask:0xf bound_ctrl:1
	v_add_f32_dpp v55, v55, v55 quad_perm:[1,0,3,2] row_mask:0xf bank_mask:0xf bound_ctrl:1
	v_add_f32_dpp v48, v48, v48 quad_perm:[2,3,0,1] row_mask:0xf bank_mask:0xf bound_ctrl:1
	v_add_f32_dpp v49, v49, v49 quad_perm:[2,3,0,1] row_mask:0xf bank_mask:0xf bound_ctrl:1
	v_add_f32_dpp v50, v50, v50 quad_perm:[2,3,0,1] row_mask:0xf bank_mask:0xf bound_ctrl:1
	v_add_f32_dpp v51, v51, v51 quad_perm:[2,3,0,1] row_mask:0xf bank_mask:0xf bound_ctrl:1
	v_add_f32_dpp v52, v52, v52 quad_perm:[2,3,0,1] row_mask:0xf bank_mask:0xf bound_ctrl:1
	v_add_f32_dpp v53, v53, v53 quad_perm:[2,3,0,1] row_mask:0xf bank_mask:0xf bound_ctrl:1
	v_add_f32_dpp v54, v54, v54 quad_perm:[2,3,0,1] row_mask:0xf bank_mask:0xf bound_ctrl:1
	v_add_f32_dpp v55, v55, v55 quad_perm:[2,3,0,1] row_mask:0xf bank_mask:0xf bound_ctrl:1
	v_add_f32_dpp v48, v48, v48 row_half_mirror row_mask:0xf bank_mask:0xf bound_ctrl:1
	v_add_f32_dpp v49, v49, v49 row_half_mirror row_mask:0xf bank_mask:0xf bound_ctrl:1
	v_add_f32_dpp v50, v50, v50 row_half_mirror row_mask:0xf bank_mask:0xf bound_ctrl:1
	v_add_f32_dpp v51, v51, v51 row_half_mirror row_mask:0xf bank_mask:0xf bound_ctrl:1
	v_add_f32_dpp v52, v52, v52 row_half_mirror row_mask:0xf bank_mask:0xf bound_ctrl:1
	v_add_f32_dpp v53, v53, v53 row_half_mirror row_mask:0xf bank_mask:0xf bound_ctrl:1
	v_add_f32_dpp v54, v54, v54 row_half_mirror row_mask:0xf bank_mask:0xf bound_ctrl:1
	v_add_f32_dpp v55, v55, v55 row_half_mirror row_mask:0xf bank_mask:0xf bound_ctrl:1
	v_add_f32_dpp v48, v48, v48 row_mirror row_mask:0xf bank_mask:0xf bound_ctrl:1
	v_add_f32_dpp v49, v49, v49 row_mirror row_mask:0xf bank_mask:0xf bound_ctrl:1
	v_add_f32_dpp v50, v50, v50 row_mirror row_mask:0xf bank_mask:0xf bound_ctrl:1
	v_add_f32_dpp v51, v51, v51 row_mirror row_mask:0xf bank_mask:0xf bound_ctrl:1
	v_add_f32_dpp v52, v52, v52 row_mirror row_mask:0xf bank_mask:0xf bound_ctrl:1
	v_add_f32_dpp v53, v53, v53 row_mirror row_mask:0xf bank_mask:0xf bound_ctrl:1
; #define LAS __attribute__((address_space(3)))
; __device__ __forceinline__ float bf2f(bf16 v) { return __uint_as_float(((unsigned)v) << 16); }
; __device__ __forceinline__ unsigned f2bf(float f) { unsigned u = __float_as_uint(f); return (u + 0x7fffu + ((u >> 16) & 1u)) >> 16; }
; __device__ __forceinline__ float siluf_(float x) { return x / (1.0f + __expf(-x)); }
; __device__ __forceinline__ int wy_producer_task(const Ctx& c, int l, int tk, WyPre& P, unsigned* head) {
;     ...
; #pragma unroll
;     for (int j = 0; j < 3; ++j) { float xv[11];
; #pragma unroll
;         for (int r = 0; r < 11; ++r) xv[r] = bf2f((bf16)P.hx[j][r]);
; #pragma unroll
;         for (int r = 0; r < 8; ++r) { const int i = 8 * wid + r;
;             float y = siluf_(P.cw[j][0] * xv[r] + P.cw[j][1] * xv[r + 1] + P.cw[j][2] * xv[r + 2] + P.cw[j][3] * xv[r + 3]);
;             if (j < 2) y *= rsqrtf(wave_sum_fast(y * y) + RMS_EPS) * (j == 0 ? 0.125f : 1.0f);
;             if (j == 0) QF[i * 65 + lane] = y;
;             else if (j == 1) { KF[i * 65 + lane] = y; *(LAS bf16*)(KIMG + (lane >> 3) * 1024 + i * 16 + (lane & 7) * 2) = (bf16)f2bf(y); }
	v_add_f32_dpp v54, v54, v54 row_mirror row_mask:0xf bank_mask:0xf bound_ctrl:1
	v_add_f32_dpp v55, v55, v55 row_mirror row_mask:0xf bank_mask:0xf bound_ctrl:1
	v_permlane16_swap_b32_e32 v48, v49
	v_permlane16_swap_b32_e32 v50, v51
	v_permlane16_swap_b32_e32 v52, v53
	v_permlane16_swap_b32_e32 v54, v55
	v_add_f32_e32 v48, v48, v49
	v_add_f32_e32 v50, v50, v51
	v_add_f32_e32 v52, v52, v53
	v_add_f32_e32 v54, v54, v55
	s_nop 1
	v_permlane32_swap_b32_e32 v48, v50
	v_permlane32_swap_b32_e32 v52, v54
	v_add_f32_e32 v48, v48, v50
	v_add_f32_e32 v52, v52, v54
	v_add_f32_e32 v48, 0x358637bd, v48
	v_add_f32_e32 v52, 0x358637bd, v52
	v_rsq_f32_e32 v48, v48
	v_rsq_f32_e32 v52, v52
	s_nop 0
	v_mul_f32_e32 v48, 0x3e000000, v48
	v_mul_f32_e32 v52, 0x3e000000, v52
	s_nop 1
	v_readlane_b32 s2, v48, 0
	v_readlane_b32 s3, v48, 16
	v_readlane_b32 s6, v48, 32
	v_readlane_b32 s7, v48, 48
	v_mul_f32_e32 v32, s2, v32
	v_mul_f32_e32 v33, s3, v33
	v_mul_f32_e32 v34, s6, v34
	v_mul_f32_e32 v35, s7, v35
	v_readlane_b32 s2, v52, 0
	v_readlane_b32 s3, v52, 16
	v_readlane_b32 s6, v52, 32
	v_readlane_b32 s7, v52, 48
	v_mul_f32_e32 v36, s2, v36
	v_mul_f32_e32 v37, s3, v37
	v_mul_f32_e32 v38, s6, v38
	v_mul_f32_e32 v39, s7, v39
	ds_write_b32 v2, v32 offset:16640
	ds_write_b32 v2, v33 offset:16900
	ds_write_b32 v2, v34 offset:17160
	ds_write_b32 v2, v35 offset:17420
	ds_write_b32 v2, v36 offset:17680
	ds_write_b32 v2, v37 offset:17940
	ds_write_b32 v2, v38 offset:18200
	ds_write_b32 v2, v39 offset:18460
	s_waitcnt vmcnt(4)
	v_and_b32_e32 v20, 0xffff0000, v119
	v_lshlrev_b32_e32 v21, 16, v119
	v_and_b32_e32 v22, 0xffff0000, v118
	v_lshlrev_b32_e32 v23, 16, v118
	v_and_b32_e32 v24, 0xffff0000, v120
	v_lshlrev_b32_e32 v25, 16, v120
	v_and_b32_e32 v26, 0xffff0000, v121
	v_lshlrev_b32_e32 v27, 16, v121
	v_and_b32_e32 v28, 0xffff0000, v122
	v_lshlrev_b32_e32 v29, 16, v122
	v_lshlrev_b32_e32 v30, 16, v96
	v_mul_f32_e32 v32, v91, v20
	v_mul_f32_e32 v33, v91, v21
	v_mul_f32_e32 v34, v91, v22
	v_mul_f32_e32 v35, v91, v23
	v_mul_f32_e32 v36, v91, v24
	v_mul_f32_e32 v37, v91, v25
	v_mul_f32_e32 v38, v91, v26
	v_mul_f32_e32 v39, v91, v27
	v_fmac_f32_e32 v32, v90, v21
	v_fmac_f32_e32 v33, v90, v22
	v_fmac_f32_e32 v34, v90, v23
	v_fmac_f32_e32 v35, v90, v24
	v_fmac_f32_e32 v36, v90, v25
	v_fmac_f32_e32 v37, v90, v26
	v_fmac_f32_e32 v38, v90, v27
	v_fmac_f32_e32 v39, v90, v28
	v_fmac_f32_e32 v32, v93, v22
	v_fmac_f32_e32 v33, v93, v23
	v_fmac_f32_e32 v34, v93, v24
	v_fmac_f32_e32 v35, v93, v25
	v_fmac_f32_e32 v36, v93, v26
	v_fmac_f32_e32 v37, v93, v27
	v_fmac_f32_e32 v38, v93, v28
	v_fmac_f32_e32 v39, v93, v29
	v_fmac_f32_e32 v32, v92, v23
	v_fmac_f32_e32 v33, v92, v24
	v_fmac_f32_e32 v34, v92, v25
	v_fmac_f32_e32 v35, v92, v26
	v_fmac_f32_e32 v36, v92, v27
	v_fmac_f32_e32 v37, v92, v28
	v_fmac_f32_e32 v38, v92, v29
	v_fmac_f32_e32 v39, v92, v30
	v_pk_mul_f32 v[40:41], v[32:33], v[66:67] op_sel_hi:[1,0]
	v_pk_mul_f32 v[42:43], v[34:35], v[66:67] op_sel_hi:[1,0]
	v_pk_mul_f32 v[44:45], v[36:37], v[66:67] op_sel_hi:[1,0]
	v_pk_mul_f32 v[46:47], v[38:39], v[66:67] op_sel_hi:[1,0]
	v_exp_f32_e32 v40, v40
	v_exp_f32_e32 v41, v41
	v_exp_f32_e32 v42, v42
	v_exp_f32_e32 v43, v43
	v_exp_f32_e32 v44, v44
	v_exp_f32_e32 v45, v45
	v_exp_f32_e32 v46, v46
	v_exp_f32_e32 v47, v47
	v_pk_add_f32 v[40:41], v[40:41], v[66:67] op_sel:[0,1] op_sel_hi:[1,1]
	v_pk_add_f32 v[42:43], v[42:43], v[66:67] op_sel:[0,1] op_sel_hi:[1,1]
	v_pk_add_f32 v[44:45], v[44:45], v[66:67] op_sel:[0,1] op_sel_hi:[1,1]
	v_pk_add_f32 v[46:47], v[46:47], v[66:67] op_sel:[0,1] op_sel_hi:[1,1]
	v_rcp_f32_e32 v40, v40
	v_rcp_f32_e32 v41, v41
	v_rcp_f32_e32 v42, v42
	v_rcp_f32_e32 v43, v43
	v_rcp_f32_e32 v44, v44
	v_rcp_f32_e32 v45, v45
	v_rcp_f32_e32 v46, v46
	v_rcp_f32_e32 v47, v47
	v_pk_mul_f32 v[32:33], v[32:33], v[40:41]
	v_pk_mul_f32 v[34:35], v[34:35], v[42:43]
	v_pk_mul_f32 v[36:37], v[36:37], v[44:45]
	v_pk_mul_f32 v[38:39], v[38:39], v[46:47]
	v_pk_mul_f32 v[48:49], v[32:33], v[32:33]
	v_pk_mul_f32 v[50:51], v[34:35], v[34:35]
	v_pk_mul_f32 v[52:53], v[36:37], v[36:37]
	v_pk_mul_f32 v[54:55], v[38:39], v[38:39]
	v_add_f32_dpp v48, v48, v48 quad_perm:[1,0,3,2] row_mask:0xf bank_mask:0xf bound_ctrl:1
	v_add_f32_dpp v49, v49, v49 quad_perm:[1,0,3,2] row_mask:0xf bank_mask:0xf bound_ctrl:1
	v_add_f32_dpp v50, v50, v50 quad_perm:[1,0,3,2] row_mask:0xf bank_mask:0xf bound_ctrl:1
	v_add_f32_dpp v51, v51, v51 quad_perm:[1,0,3,2] row_mask:0xf bank_mask:0xf bound_ctrl:1
	v_add_f32_dpp v52, v52, v52 quad_perm:[1,0,3,2] row_mask:0xf bank_mask:0xf bound_ctrl:1
	v_add_f32_dpp v53, v53, v53 quad_perm:[1,0,3,2] row_mask:0xf bank_mask:0xf bound_ctrl:1
	v_add_f32_dpp v54, v54, v54 quad_perm:[1,0,3,2] row_mask:0xf bank_mask:0xf bound_ctrl:1
	v_add_f32_dpp v55, v55, v55 quad_perm:[1,0,3,2] row_mask:0xf bank_mask:0xf bound_ctrl:1
	v_add_f32_dpp v48, v48, v48 quad_perm:[2,3,0,1] row_mask:0xf bank_mask:0xf bound_ctrl:1
	v_add_f32_dpp v49, v49, v49 quad_perm:[2,3,0,1] row_mask:0xf bank_mask:0xf bound_ctrl:1
	v_add_f32_dpp v50, v50, v50 quad_perm:[2,3,0,1] row_mask:0xf bank_mask:0xf bound_ctrl:1
	v_add_f32_dpp v51, v51, v51 quad_perm:[2,3,0,1] row_mask:0xf bank_mask:0xf bound_ctrl:1
	v_add_f32_dpp v52, v52, v52 quad_perm:[2,3,0,1] row_mask:0xf bank_mask:0xf bound_ctrl:1
	v_add_f32_dpp v53, v53, v53 quad_perm:[2,3,0,1] row_mask:0xf bank_mask:0xf bound_ctrl:1
	v_add_f32_dpp v54, v54, v54 quad_perm:[2,3,0,1] row_mask:0xf bank_mask:0xf bound_ctrl:1
	v_add_f32_dpp v55, v55, v55 quad_perm:[2,3,0,1] row_mask:0xf bank_mask:0xf bound_ctrl:1
	v_add_f32_dpp v48, v48, v48 row_half_mirror row_mask:0xf bank_mask:0xf bound_ctrl:1
; #define LAS __attribute__((address_space(3)))
; __device__ __forceinline__ float bf2f(bf16 v) { return __uint_as_float(((unsigned)v) << 16); }
; __device__ __forceinline__ unsigned f2bf(float f) { unsigned u = __float_as_uint(f); return (u + 0x7fffu + ((u >> 16) & 1u)) >> 16; }
; __device__ __forceinline__ float siluf_(float x) { return x / (1.0f + __expf(-x)); }
; __device__ __forceinline__ int wy_producer_task(const Ctx& c, int l, int tk, WyPre& P, unsigned* head) {
;     ...
; #pragma unroll
;     for (int j = 0; j < 3; ++j) { float xv[11];
; #pragma unroll
;         for (int r = 0; r < 11; ++r) xv[r] = bf2f((bf16)P.hx[j][r]);
; #pragma unroll
;         for (int r = 0; r < 8; ++r) { const int i = 8 * wid + r;
;             float y = siluf_(P.cw[j][0] * xv[r] + P.cw[j][1] * xv[r + 1] + P.cw[j][2] * xv[r + 2] + P.cw[j][3] * xv[r + 3]);
;             if (j < 2) y *= rsqrtf(wave_sum_fast(y * y) + RMS_EPS) * (j == 0 ? 0.125f : 1.0f);
;             if (j == 0) QF[i * 65 + lane] = y;
;             else if (j == 1) { KF[i * 65 + lane] = y; *(LAS bf16*)(KIMG + (lane >> 3) * 1024 + i * 16 + (lane & 7) * 2) = (bf16)f2bf(y); }
;             else VF[i * 65 + lane] = y; } }
	v_add_f32_dpp v49, v49, v49 row_half_mirror row_mask:0xf bank_mask:0xf bound_ctrl:1
	v_add_f32_dpp v50, v50, v50 row_half_mirror row_mask:0xf bank_mask:0xf bound_ctrl:1
	v_add_f32_dpp v51, v51, v51 row_half_mirror row_mask:0xf bank_mask:0xf bound_ctrl:1
	v_add_f32_dpp v52, v52, v52 row_half_mirror row_mask:0xf bank_mask:0xf bound_ctrl:1
	v_add_f32_dpp v53, v53, v53 row_half_mirror row_mask:0xf bank_mask:0xf bound_ctrl:1
	v_add_f32_dpp v54, v54, v54 row_half_mirror row_mask:0xf bank_mask:0xf bound_ctrl:1
	v_add_f32_dpp v55, v55, v55 row_half_mirror row_mask:0xf bank_mask:0xf bound_ctrl:1
	v_add_f32_dpp v48, v48, v48 row_mirror row_mask:0xf bank_mask:0xf bound_ctrl:1
	v_add_f32_dpp v49, v49, v49 row_mirror row_mask:0xf bank_mask:0xf bound_ctrl:1
	v_add_f32_dpp v50, v50, v50 row_mirror row_mask:0xf bank_mask:0xf bound_ctrl:1
	v_add_f32_dpp v51, v51, v51 row_mirror row_mask:0xf bank_mask:0xf bound_ctrl:1
	v_add_f32_dpp v52, v52, v52 row_mirror row_mask:0xf bank_mask:0xf bound_ctrl:1
	v_add_f32_dpp v53, v53, v53 row_mirror row_mask:0xf bank_mask:0xf bound_ctrl:1
	v_add_f32_dpp v54, v54, v54 row_mirror row_mask:0xf bank_mask:0xf bound_ctrl:1
	v_add_f32_dpp v55, v55, v55 row_mirror row_mask:0xf bank_mask:0xf bound_ctrl:1
	v_permlane16_swap_b32_e32 v48, v49
	v_permlane16_swap_b32_e32 v50, v51
	v_permlane16_swap_b32_e32 v52, v53
	v_permlane16_swap_b32_e32 v54, v55
	v_add_f32_e32 v48, v48, v49
	v_add_f32_e32 v50, v50, v51
	v_add_f32_e32 v52, v52, v53
	v_add_f32_e32 v54, v54, v55
	s_nop 1
	v_permlane32_swap_b32_e32 v48, v50
	v_permlane32_swap_b32_e32 v52, v54
	v_add_f32_e32 v48, v48, v50
	v_add_f32_e32 v52, v52, v54
	v_add_f32_e32 v48, 0x358637bd, v48
	v_add_f32_e32 v52, 0x358637bd, v52
	v_rsq_f32_e32 v48, v48
	v_rsq_f32_e32 v52, v52
	s_nop 0
	s_nop 1
	v_readlane_b32 s2, v48, 0
	v_readlane_b32 s3, v48, 16
	v_readlane_b32 s6, v48, 32
	v_readlane_b32 s7, v48, 48
	v_mul_f32_e32 v32, s2, v32
	v_mul_f32_e32 v33, s3, v33
	v_mul_f32_e32 v34, s6, v34
	v_mul_f32_e32 v35, s7, v35
	v_readlane_b32 s2, v52, 0
	v_readlane_b32 s3, v52, 16
	v_readlane_b32 s6, v52, 32
	v_readlane_b32 s7, v52, 48
	v_mul_f32_e32 v36, s2, v36
	v_mul_f32_e32 v37, s3, v37
	v_mul_f32_e32 v38, s6, v38
	v_mul_f32_e32 v39, s7, v39
	ds_write_b32 v2, v32 offset:0
	ds_write_b32 v2, v33 offset:260
	ds_write_b32 v2, v34 offset:520
	ds_write_b32 v2, v35 offset:780
	ds_write_b32 v2, v36 offset:1040
	ds_write_b32 v2, v37 offset:1300
	ds_write_b32 v2, v38 offset:1560
	ds_write_b32 v2, v39 offset:1820
	v_cvt_pk_bf16_f32 v40, v32, v33
	v_cvt_pk_bf16_f32 v41, v34, v35
	v_cvt_pk_bf16_f32 v42, v36, v37
	v_cvt_pk_bf16_f32 v43, v38, v39
	ds_write_b16 v4, v40 offset:0
	ds_write_b16_d16_hi v4, v40 offset:16
	ds_write_b16 v4, v41 offset:32
	ds_write_b16_d16_hi v4, v41 offset:48
	ds_write_b16 v4, v42 offset:64
	ds_write_b16_d16_hi v4, v42 offset:80
	ds_write_b16 v4, v43 offset:96
	ds_write_b16_d16_hi v4, v43 offset:112
	s_waitcnt vmcnt(0)
	v_lshlrev_b32_e32 v20, 16, v98
	v_lshlrev_b32_e32 v21, 16, v97
	v_lshlrev_b32_e32 v22, 16, v100
	v_lshlrev_b32_e32 v23, 16, v99
	v_lshlrev_b32_e32 v24, 16, v101
	v_lshlrev_b32_e32 v25, 16, v102
	v_lshlrev_b32_e32 v26, 16, v104
	v_lshlrev_b32_e32 v27, 16, v103
	v_lshlrev_b32_e32 v28, 16, v105
	v_lshlrev_b32_e32 v29, 16, v106
	v_lshlrev_b32_e32 v30, 16, v107
	v_mul_f32_e32 v32, v108, v20
	v_mul_f32_e32 v33, v108, v21
	v_mul_f32_e32 v34, v108, v22
	v_mul_f32_e32 v35, v108, v23
	v_mul_f32_e32 v36, v108, v24
	v_mul_f32_e32 v37, v108, v25
	v_mul_f32_e32 v38, v108, v26
	v_mul_f32_e32 v39, v108, v27
	v_fmac_f32_e32 v32, v110, v21
	v_fmac_f32_e32 v33, v110, v22
	v_fmac_f32_e32 v34, v110, v23
	v_fmac_f32_e32 v35, v110, v24
	v_fmac_f32_e32 v36, v110, v25
	v_fmac_f32_e32 v37, v110, v26
	v_fmac_f32_e32 v38, v110, v27
	v_fmac_f32_e32 v39, v110, v28
	v_fmac_f32_e32 v32, v112, v22
	v_fmac_f32_e32 v33, v112, v23
	v_fmac_f32_e32 v34, v112, v24
	v_fmac_f32_e32 v35, v112, v25
	v_fmac_f32_e32 v36, v112, v26
	v_fmac_f32_e32 v37, v112, v27
	v_fmac_f32_e32 v38, v112, v28
	v_fmac_f32_e32 v39, v112, v29
	v_fmac_f32_e32 v32, v113, v23
	v_fmac_f32_e32 v33, v113, v24
	v_fmac_f32_e32 v34, v113, v25
	v_fmac_f32_e32 v35, v113, v26
	v_fmac_f32_e32 v36, v113, v27
	v_fmac_f32_e32 v37, v113, v28
	v_fmac_f32_e32 v38, v113, v29
	v_fmac_f32_e32 v39, v113, v30
	v_pk_mul_f32 v[40:41], v[32:33], v[66:67] op_sel_hi:[1,0]
	v_pk_mul_f32 v[42:43], v[34:35], v[66:67] op_sel_hi:[1,0]
	v_pk_mul_f32 v[44:45], v[36:37], v[66:67] op_sel_hi:[1,0]
	v_pk_mul_f32 v[46:47], v[38:39], v[66:67] op_sel_hi:[1,0]
	v_exp_f32_e32 v40, v40
	v_exp_f32_e32 v41, v41
	v_exp_f32_e32 v42, v42
	v_exp_f32_e32 v43, v43
	v_exp_f32_e32 v44, v44
	v_exp_f32_e32 v45, v45
	v_exp_f32_e32 v46, v46
	v_exp_f32_e32 v47, v47
	v_pk_add_f32 v[40:41], v[40:41], v[66:67] op_sel:[0,1] op_sel_hi:[1,1]
	v_pk_add_f32 v[42:43], v[42:43], v[66:67] op_sel:[0,1] op_sel_hi:[1,1]
	v_pk_add_f32 v[44:45], v[44:45], v[66:67] op_sel:[0,1] op_sel_hi:[1,1]
	v_pk_add_f32 v[46:47], v[46:47], v[66:67] op_sel:[0,1] op_sel_hi:[1,1]
	v_rcp_f32_e32 v40, v40
	v_rcp_f32_e32 v41, v41
	v_rcp_f32_e32 v42, v42
	v_rcp_f32_e32 v43, v43
	v_rcp_f32_e32 v44, v44
	v_rcp_f32_e32 v45, v45
	v_rcp_f32_e32 v46, v46
	v_rcp_f32_e32 v47, v47
	v_pk_mul_f32 v[32:33], v[32:33], v[40:41]
	v_pk_mul_f32 v[34:35], v[34:35], v[42:43]
	v_pk_mul_f32 v[36:37], v[36:37], v[44:45]
	v_pk_mul_f32 v[38:39], v[38:39], v[46:47]
	ds_write_b32 v3, v32 offset:0
	ds_write_b32 v3, v33 offset:260
	ds_write_b32 v3, v34 offset:520
	ds_write_b32 v3, v35 offset:780
	ds_write_b32 v3, v36 offset:1040
	ds_write_b32 v3, v37 offset:1300
	ds_write_b32 v3, v38 offset:1560
	ds_write_b32 v3, v39 offset:1820
	s_and_b64 vcc, exec, s[38:39]
	s_cbranch_vccz .LBB0_1093
	s_and_saveexec_b64 s[2:3], s[4:5]
